# in-proj sample GEMM: the two row-statistics loads after the split-K reduction issued together with the LDS reads
# baseline (speedup 1.0000x reference)
.LBB0_673:
	s_and_b32 s6, s14, 0xffffffe0
	v_or_b32_e32 v6, s6, v5
	v_ashrrev_i32_e32 v7, 31, v6
	s_and_b32 s4, s12, 0x70
	v_lshlrev_b64 v[6:7], 11, v[6:7]
	v_or_b32_e32 v19, s4, v5
	v_lshl_add_u64 v[40:41], v[14:15], 0, v[6:7]
	s_mov_b32 s4, 0x8000
	v_lshlrev_b32_e32 v0, 11, v19
	v_add_co_u32_e32 v42, vcc, s4, v40
	v_lshl_add_u64 v[38:39], v[2:3], 0, v[0:1]
	s_nop 0
	v_addc_co_u32_e32 v43, vcc, 0, v41, vcc
	global_load_dwordx4 v[6:9], v[38:39], off
	global_load_dwordx4 v[10:13], v[40:41], off
	s_waitcnt lgkmcnt(0)
	global_load_dwordx4 v[22:25], v[42:43], off
	global_load_dwordx4 v[26:29], v[40:41], off offset:64
	global_load_dwordx4 v[30:33], v[38:39], off offset:64
	v_add_u32_e32 v0, s11, v21
	s_andn2_b64 vcc, exec, s[2:3]
	s_waitcnt vmcnt(0)
	v_mfma_f32_16x16x32_bf16 v[10:13], v[10:13], v[6:9], 0
	s_waitcnt lgkmcnt(0)
	v_mfma_f32_16x16x32_bf16 v[6:9], v[22:25], v[6:9], 0
	global_load_dwordx4 v[22:25], v[42:43], off offset:64
	v_mfma_f32_16x16x32_bf16 v[10:13], v[26:29], v[30:33], v[10:13]
	global_load_dwordx4 v[26:29], v[40:41], off offset:128
	global_load_dwordx4 v[34:37], v[38:39], off offset:128
	s_waitcnt vmcnt(0) lgkmcnt(0)
	v_mfma_f32_16x16x32_bf16 v[10:13], v[26:29], v[34:37], v[10:13]
	v_mfma_f32_16x16x32_bf16 v[6:9], v[22:25], v[30:33], v[6:9]
	global_load_dwordx4 v[22:25], v[42:43], off offset:128
	global_load_dwordx4 v[26:29], v[40:41], off offset:192
	global_load_dwordx4 v[30:33], v[42:43], off offset:192
	s_waitcnt vmcnt(0) lgkmcnt(0)
	v_mfma_f32_16x16x32_bf16 v[22:25], v[22:25], v[34:37], v[6:9]
	global_load_dwordx4 v[34:37], v[38:39], off offset:192
	s_waitcnt vmcnt(0) lgkmcnt(0)
	v_mfma_f32_16x16x32_bf16 v[6:9], v[26:29], v[34:37], v[10:13]
	v_mfma_f32_16x16x32_bf16 v[10:13], v[30:33], v[34:37], v[22:25]
	s_nop 6
	ds_write_b128 v0, v[6:9]
	ds_write_b128 v0, v[10:13] offset:1024
	s_waitcnt lgkmcnt(0)
	s_barrier
	s_cbranch_vccnz .LBB0_672
	v_lshlrev_b32_e32 v0, 7, v19
	s_ashr_i32 s7, s6, 31
	ds_read_b128 v[64:67], v21 offset:2048
	ds_read_b128 v[68:71], v21 offset:3072
	ds_read_b128 v[72:75], v21 offset:4096
	ds_read_b128 v[76:79], v21 offset:5120
	ds_read_b128 v[80:83], v21 offset:6144
	ds_read_b128 v[84:87], v21 offset:7168
	ds_read_b128 v[88:91], v21 offset:8192
	ds_read_b128 v[92:95], v21 offset:9216
	ds_read_b128 v[96:99], v21 offset:10240
	ds_read_b128 v[100:103], v21 offset:11264
	ds_read_b128 v[104:107], v21 offset:12288
	ds_read_b128 v[108:111], v21 offset:13312
	ds_read_b128 v[112:115], v21 offset:14336
	ds_read_b128 v[116:119], v21 offset:15360
	v_lshl_add_u64 v[124:125], v[16:17], 0, v[0:1]
	global_load_dwordx4 v[120:123], v[124:125], off
	global_load_dwordx4 v[128:131], v[124:125], off offset:16
	s_waitcnt lgkmcnt(13)
	v_pk_add_f32 v[24:25], v[8:9], v[66:67]
	v_pk_add_f32 v[22:23], v[6:7], v[64:65]
	s_waitcnt lgkmcnt(12)
	v_pk_add_f32 v[12:13], v[12:13], v[70:71]
	v_pk_add_f32 v[10:11], v[10:11], v[68:69]
	s_waitcnt lgkmcnt(11)
	v_pk_add_f32 v[24:25], v[24:25], v[74:75]
	v_pk_add_f32 v[22:23], v[22:23], v[72:73]
	s_waitcnt lgkmcnt(10)
	v_pk_add_f32 v[12:13], v[12:13], v[78:79]
	v_pk_add_f32 v[10:11], v[10:11], v[76:77]
	s_waitcnt lgkmcnt(9)
	v_pk_add_f32 v[24:25], v[24:25], v[82:83]
	v_pk_add_f32 v[22:23], v[22:23], v[80:81]
	s_waitcnt lgkmcnt(8)
	v_pk_add_f32 v[12:13], v[12:13], v[86:87]
	v_pk_add_f32 v[10:11], v[10:11], v[84:85]
	s_waitcnt lgkmcnt(7)
	v_pk_add_f32 v[24:25], v[24:25], v[90:91]
	v_pk_add_f32 v[22:23], v[22:23], v[88:89]
	s_waitcnt lgkmcnt(6)
	v_pk_add_f32 v[12:13], v[12:13], v[94:95]
	v_pk_add_f32 v[10:11], v[10:11], v[92:93]
	s_waitcnt lgkmcnt(5)
	v_pk_add_f32 v[24:25], v[24:25], v[98:99]
	v_pk_add_f32 v[22:23], v[22:23], v[96:97]
	s_waitcnt lgkmcnt(4)
	v_pk_add_f32 v[12:13], v[12:13], v[102:103]
	v_pk_add_f32 v[10:11], v[10:11], v[100:101]
	s_waitcnt lgkmcnt(3)
	v_pk_add_f32 v[24:25], v[24:25], v[106:107]
	v_pk_add_f32 v[22:23], v[22:23], v[104:105]
	s_waitcnt lgkmcnt(2)
	v_pk_add_f32 v[12:13], v[12:13], v[110:111]
	v_pk_add_f32 v[26:27], v[10:11], v[108:109]
	s_waitcnt lgkmcnt(1)
	v_pk_add_f32 v[28:29], v[24:25], v[114:115]
	v_pk_add_f32 v[30:31], v[22:23], v[112:113]
	s_waitcnt lgkmcnt(0)
	v_pk_add_f32 v[10:11], v[12:13], v[118:119]
	v_pk_add_f32 v[12:13], v[26:27], v[116:117]
	v_lshl_add_u64 v[22:23], v[16:17], 0, v[0:1]
	s_waitcnt vmcnt(0)
	v_mov_b32_e32 v6, v120
	v_mov_b32_e32 v7, v121
	v_mov_b32_e32 v8, v122
	v_mov_b32_e32 v9, v123
	v_mov_b32_e32 v22, v128
	v_mov_b32_e32 v23, v129
	v_mov_b32_e32 v24, v130
	v_mov_b32_e32 v25, v131
	s_waitcnt vmcnt(0) lgkmcnt(0)
	v_mov_b32_e32 v26, v6
	v_mov_b32_e32 v27, v22
	v_mov_b32_e32 v22, v7
	v_pk_add_f32 v[6:7], v[26:27], v[22:23]
	v_mov_b32_e32 v22, v8
	v_mov_b32_e32 v23, v24
	v_mov_b32_e32 v24, v9
	v_pk_add_f32 v[8:9], v[22:23], v[24:25]
	s_nop 0
	v_pk_add_f32 v[6:7], v[6:7], v[8:9]
	s_nop 0
	v_add_f32_e32 v0, v6, v7
	ds_bpermute_b32 v6, v174, v0
	s_waitcnt lgkmcnt(0)
	v_add_f32_e32 v0, v0, v6
	ds_bpermute_b32 v6, v175, v0
	s_waitcnt lgkmcnt(0)
	v_add_f32_e32 v0, v0, v6
	v_fmamk_f32 v0, v0, 0x3a800000, v219
	v_cmp_gt_f32_e32 vcc, s85, v0
	v_mul_f32_e32 v6, 0x4f800000, v0
	s_nop 0
	v_cndmask_b32_e32 v0, v0, v6, vcc
	v_sqrt_f32_e32 v6, v0
	s_nop 0
	v_add_u32_e32 v7, -1, v6
	v_fma_f32 v8, -v7, v6, v0
	v_cmp_ge_f32_e64 s[4:5], 0, v8
	v_add_u32_e32 v8, 1, v6
	s_nop 0
	v_cndmask_b32_e64 v7, v6, v7, s[4:5]
	v_fma_f32 v6, -v8, v6, v0
	v_cmp_lt_f32_e64 s[4:5], 0, v6
	s_nop 1
	v_cndmask_b32_e64 v6, v7, v8, s[4:5]
	v_mul_f32_e32 v7, 0x37800000, v6
	v_cndmask_b32_e32 v6, v6, v7, vcc
	v_cmp_class_f32_e32 vcc, v0, v221
	s_nop 1
	v_cndmask_b32_e32 v0, v6, v0, vcc
	v_div_scale_f32 v6, s[4:5], v0, v0, 1.0
	v_rcp_f32_e32 v7, v6
	s_nop 0
	v_fma_f32 v8, -v6, v7, 1.0
	v_fmac_f32_e32 v7, v8, v7
	v_div_scale_f32 v8, vcc, 1.0, v0, 1.0
	v_mul_f32_e32 v9, v8, v7
	v_fma_f32 v20, -v6, v9, v8
	v_fmac_f32_e32 v9, v20, v7
	v_fma_f32 v6, -v6, v9, v8
	v_div_fmas_f32 v6, v6, v7, v9
	v_div_fixup_f32 v20, v6, v0, 1.0
	v_mul_u32_u24_e32 v0, 0x700, v19
	v_lshlrev_b32_e32 v0, 2, v0
	v_lshl_add_u64 v[22:23], s[0:1], 0, v[0:1]
	v_lshl_add_u64 v[22:23], s[6:7], 2, v[22:23]
	v_mov_b32_e32 v19, v1
	v_pk_mul_f32 v[8:9], v[28:29], v[20:21] op_sel_hi:[1,0]
	v_pk_mul_f32 v[6:7], v[30:31], v[20:21] op_sel_hi:[1,0]
	v_lshl_add_u64 v[22:23], v[22:23], 0, v[18:19]
	global_store_dwordx4 v[22:23], v[6:9], off
	s_nop 1
	v_pk_mul_f32 v[8:9], v[10:11], v[20:21] op_sel_hi:[1,0]
	v_pk_mul_f32 v[6:7], v[12:13], v[20:21] op_sel_hi:[1,0]
	global_store_dwordx4 v[22:23], v[6:9], off offset:64
	s_branch .LBB0_672
